# hyena staging: first four tap loads no longer serialized by per-load vmcnt(0)
# baseline (speedup 1.0000x reference)
; DI void hyena_unit(const Inputs& in, int l, unsigned char* ws, int half, int c, LAS unsigned char* lds, int tid) {
;     ...
;     { u32x4 fv[5], zv[8];
; #pragma unroll
;       for (int k = 0; k < 5; ++k) { const int i = tid + 512 * k, cp = i >= nfr, kk = cp ? i - nfr : i; fv[k] = (u32x4){0u, 0u, 0u, 0u};
;           if (i < 2 * nfr && kk < 2 * L / 8) fv[k] = *(const u32x4*)((cp ? FRO : FR) + kk * 8);
;           if (cp && kk == 2 * L / 8 - 1) fv[k].w &= 0xffffu; }
; #pragma unroll
;       for (int k = 0; k < 8; ++k) { const int i = tid + 512 * k, b = i / cpr, j = i % cpr, m = j * 8 - 1024; zv[k] = (u32x4){0u, 0u, 0u, 0u};
;           if (i < NB * cpr && m >= 0 && m < L) zv[k] = *(const u32x4*)(ZT + (size_t)(b * 512 + c) * L + m); }
.LBB0_620:
	s_or_b64 exec, exec, vcc
	s_mov_b64 vcc, s[4:5]
	v_mov_b32_e32 v1, 0
	v_mov_b32_e32 v2, 0
	v_mov_b32_e32 v3, 0
	s_and_saveexec_b64 vcc, s[48:49]
	s_cbranch_execz .LBB0_622
	v_lshl_add_u64 v[0:1], s[74:75], 0, v[54:55]
	v_lshl_add_u64 v[0:1], v[56:57], 1, v[0:1]
	global_load_dwordx4 v[0:3], v[0:1], off
.LBB0_622:
	s_or_b64 exec, exec, vcc
	s_mov_b64 vcc, s[8:9]
	v_mov_b32_e32 v8, 0
	v_mov_b32_e32 v12, 0
	v_mov_b32_e32 v13, 0
	v_mov_b32_e32 v14, 0
	v_mov_b32_e32 v15, 0
	s_and_saveexec_b64 vcc, s[50:51]
	s_cbranch_execz .LBB0_624
	v_lshl_add_u64 v[10:11], s[74:75], 0, v[58:59]
	v_lshl_add_u64 v[10:11], v[60:61], 1, v[10:11]
	global_load_dwordx4 v[12:15], v[10:11], off
.LBB0_624:
	s_or_b64 exec, exec, vcc
	v_mov_b32_e32 v9, 0
	v_mov_b32_e32 v10, 0
	v_mov_b32_e32 v11, 0
	s_and_saveexec_b64 vcc, s[52:53]
	s_cbranch_execz .LBB0_626
	v_lshl_add_u64 v[8:9], s[74:75], 0, v[62:63]
	v_lshl_add_u64 v[8:9], v[64:65], 1, v[8:9]
	global_load_dwordx4 v[8:11], v[8:9], off
.LBB0_626:
	s_or_b64 exec, exec, vcc
	v_mov_b32_e32 v16, 0
	v_mov_b32_e32 v20, 0
	v_mov_b32_e32 v21, 0
	v_mov_b32_e32 v22, 0
	v_mov_b32_e32 v23, 0
	s_and_saveexec_b64 vcc, s[54:55]
	s_cbranch_execz .LBB0_628
	v_lshl_add_u64 v[18:19], s[74:75], 0, v[66:67]
	v_lshl_add_u64 v[18:19], v[68:69], 1, v[18:19]
	global_load_dwordx4 v[20:23], v[18:19], off

; #define LAS __attribute__((address_space(3)))
; DI void hyena_unit(const Inputs& in, int l, unsigned char* ws, int half, int c, LAS unsigned char* lds, int tid) {
;     ...
;       for (int k = 0; k < 5; ++k) { const int i = tid + 512 * k, cp = i >= nfr, kk = cp ? i - nfr : i; fv[k] = (u32x4){0u, 0u, 0u, 0u};
;           if (i < 2 * nfr && kk < 2 * L / 8) fv[k] = *(const u32x4*)((cp ? FRO : FR) + kk * 8);
;           if (cp && kk == 2 * L / 8 - 1) fv[k].w &= 0xffffu; }
; #pragma unroll
;       for (int k = 0; k < 8; ++k) { const int i = tid + 512 * k, b = i / cpr, j = i % cpr, m = j * 8 - 1024; zv[k] = (u32x4){0u, 0u, 0u, 0u};
;           if (i < NB * cpr && m >= 0 && m < L) zv[k] = *(const u32x4*)(ZT + (size_t)(b * 512 + c) * L + m); }
; #pragma unroll
;       for (int k = 0; k < 5; ++k) { const int i = tid + 512 * k, cp = i >= nfr, kk = cp ? i - nfr : i; if (i < 2 * nfr) *(LAS u32x4*)(lds + cp * FRB + kk * 16) = fv[k]; }
; #pragma unroll
;       for (int k = 0; k < 8; ++k) { const int i = tid + 512 * k, b = i / cpr, j = i % cpr; if (i < NB * cpr) *(LAS u32x4*)(Zl + ((size_t)b * ZSP + (j >> 2) * 40 + (j & 3) * 8) * 2) = zv[k]; } }
.LBB0_644:
	s_or_b64 exec, exec, s[74:75]
	s_mov_b64 vcc, s[20:21]
	s_waitcnt vmcnt(0)
	v_cndmask_b32_sdwa v23, v23, v23, vcc dst_sel:DWORD dst_unused:UNUSED_PAD src0_sel:DWORD src1_sel:WORD_0
	s_mov_b64 vcc, s[4:5]
	s_nop 0
	v_cndmask_b32_sdwa v7, v7, v7, vcc dst_sel:DWORD dst_unused:UNUSED_PAD src0_sel:DWORD src1_sel:WORD_0
	s_mov_b64 vcc, s[8:9]
	s_nop 0
	v_cndmask_b32_sdwa v3, v3, v3, vcc dst_sel:DWORD dst_unused:UNUSED_PAD src0_sel:DWORD src1_sel:WORD_0
	v_and_b32_e32 v204, 0xffff, v15
	v_cndmask_b32_e64 v15, v15, v204, s[12:13]
	v_and_b32_e32 v204, 0xffff, v11
	v_cndmask_b32_e64 v11, v11, v204, s[16:17]
	s_and_saveexec_b64 s[74:75], s[2:3]
	s_cbranch_execnz .LBB0_661
	s_or_b64 exec, exec, s[74:75]
	s_and_saveexec_b64 s[74:75], s[6:7]
	s_cbranch_execnz .LBB0_662
